# vectorised conv-state copies in P2/P6 + batched normaliser scan loads in P3 passB
# speedup vs baseline: 1.1621x; 1.1621x over previous
.LBB0_452:
	v_readlane_b32 s6, v239, 0
	v_readlane_b32 s7, v239, 1
	s_load_dword s5, s[6:7], 0x10
	s_load_dword s8, s[6:7], 0x0
	s_lshl_b32 s96, s2, 9
	s_mov_b32 s4, 0x120000
	v_add_u32_e32 v0, s96, v120
	s_waitcnt lgkmcnt(0)
	s_lshr_b32 s5, s5, 16
	s_cmp_lg_u32 s5, 0
	s_cselect_b64 s[6:7], -1, 0
	s_cmp_lg_u64 s[6:7], 0
	s_addc_u32 s11, s8, 0
	s_lshl_b32 s10, s11, 9
	v_cmp_gt_i32_e32 vcc, s4, v0
	s_and_saveexec_b64 s[6:7], vcc
	s_cbranch_execz .LBB0_460
	s_mov_b32 s4, 0xaaaaaaab
	s_mov_b32 s5, 0x24000
	v_mov_b32_e32 v1, v0
.Lsdnc_loop:
	s_mov_b64 s[8:9], exec
	v_cmp_gt_u32_e64 s[12:13], s5, v1
	v_lshrrev_b32_e32 v14, 7, v1
	v_mul_hi_u32 v14, v14, s4
	v_lshrrev_b32_e32 v14, 1, v14
	v_mul_u32_u24_e32 v15, 0x180, v14
	v_sub_u32_e32 v15, v1, v15
	v_mul_hi_u32 v16, v14, s4
	v_lshrrev_b32_e32 v16, 1, v16
	v_lshl_add_u32 v5, v16, 1, v16
	v_sub_u32_e32 v5, v14, v5
	v_lshl_add_u32 v5, v16, 3, v5
	v_add_u32_e32 v5, 0x2005, v5
	v_mul_u32_u24_e32 v5, 0x3800, v5
	v_lshl_add_u32 v5, v15, 4, v5
	v_mul_u32_u24_e32 v9, 0x3000, v14
	v_lshl_add_u32 v9, v15, 5, v9
	v_add_u32_e32 v9, 0x4c7e040, v9
	v_add_u32_e32 v2, s10, v1
	v_cmp_gt_u32_e64 s[14:15], s5, v2
	v_lshrrev_b32_e32 v14, 7, v2
	v_mul_hi_u32 v14, v14, s4
	v_lshrrev_b32_e32 v14, 1, v14
	v_mul_u32_u24_e32 v15, 0x180, v14
	v_sub_u32_e32 v15, v2, v15
	v_mul_hi_u32 v16, v14, s4
	v_lshrrev_b32_e32 v16, 1, v16
	v_lshl_add_u32 v6, v16, 1, v16
	v_sub_u32_e32 v6, v14, v6
	v_lshl_add_u32 v6, v16, 3, v6
	v_add_u32_e32 v6, 0x2005, v6
	v_mul_u32_u24_e32 v6, 0x3800, v6
	v_lshl_add_u32 v6, v15, 4, v6
	v_mul_u32_u24_e32 v10, 0x3000, v14
	v_lshl_add_u32 v10, v15, 5, v10
	v_add_u32_e32 v10, 0x4c7e040, v10
	v_add_u32_e32 v3, s10, v2
	v_cmp_gt_u32_e64 s[16:17], s5, v3
	v_lshrrev_b32_e32 v14, 7, v3
	v_mul_hi_u32 v14, v14, s4
	v_lshrrev_b32_e32 v14, 1, v14
	v_mul_u32_u24_e32 v15, 0x180, v14
	v_sub_u32_e32 v15, v3, v15
	v_mul_hi_u32 v16, v14, s4
	v_lshrrev_b32_e32 v16, 1, v16
	v_lshl_add_u32 v7, v16, 1, v16
	v_sub_u32_e32 v7, v14, v7
	v_lshl_add_u32 v7, v16, 3, v7
	v_add_u32_e32 v7, 0x2005, v7
	v_mul_u32_u24_e32 v7, 0x3800, v7
	v_lshl_add_u32 v7, v15, 4, v7
	v_mul_u32_u24_e32 v11, 0x3000, v14
	v_lshl_add_u32 v11, v15, 5, v11
	v_add_u32_e32 v11, 0x4c7e040, v11
	v_add_u32_e32 v4, s10, v3
	v_cmp_gt_u32_e64 s[18:19], s5, v4
	v_lshrrev_b32_e32 v14, 7, v4
	v_mul_hi_u32 v14, v14, s4
	v_lshrrev_b32_e32 v14, 1, v14
	v_mul_u32_u24_e32 v15, 0x180, v14
	v_sub_u32_e32 v15, v4, v15
	v_mul_hi_u32 v16, v14, s4
	v_lshrrev_b32_e32 v16, 1, v16
	v_lshl_add_u32 v8, v16, 1, v16
	v_sub_u32_e32 v8, v14, v8
	v_lshl_add_u32 v8, v16, 3, v8
	v_add_u32_e32 v8, 0x2005, v8
	v_mul_u32_u24_e32 v8, 0x3800, v8
	v_lshl_add_u32 v8, v15, 4, v8
	v_mul_u32_u24_e32 v12, 0x3000, v14
	v_lshl_add_u32 v12, v15, 5, v12
	v_add_u32_e32 v12, 0x4c7e040, v12
	s_and_b64 exec, s[8:9], s[12:13]
	global_load_dwordx4 v[240:243], v5, s[30:31]
	s_and_b64 exec, s[8:9], s[14:15]
	global_load_dwordx4 v[244:247], v6, s[30:31]
	s_and_b64 exec, s[8:9], s[16:17]
	global_load_dwordx4 v[248:251], v7, s[30:31]
	s_and_b64 exec, s[8:9], s[18:19]
	global_load_dwordx4 v[252:255], v8, s[30:31]
	s_waitcnt vmcnt(0)
	s_and_b64 exec, s[8:9], s[12:13]
	v_lshlrev_b32_e32 v14, 16, v240
	v_and_b32_e32 v15, 0xffff0000, v240
	v_lshlrev_b32_e32 v16, 16, v241
	v_and_b32_e32 v17, 0xffff0000, v241
	global_store_dwordx4 v9, v[14:17], s[28:29]
	v_lshlrev_b32_e32 v240, 16, v242
	v_and_b32_e32 v241, 0xffff0000, v242
	v_lshlrev_b32_e32 v242, 16, v243
	v_and_b32_e32 v243, 0xffff0000, v243
	global_store_dwordx4 v9, v[240:243], s[28:29] offset:16
	s_nop 1
	s_and_b64 exec, s[8:9], s[14:15]
	v_lshlrev_b32_e32 v14, 16, v244
	v_and_b32_e32 v15, 0xffff0000, v244
	v_lshlrev_b32_e32 v16, 16, v245
	v_and_b32_e32 v17, 0xffff0000, v245
	global_store_dwordx4 v10, v[14:17], s[28:29]
	v_lshlrev_b32_e32 v244, 16, v246
	v_and_b32_e32 v245, 0xffff0000, v246
	v_lshlrev_b32_e32 v246, 16, v247
	v_and_b32_e32 v247, 0xffff0000, v247
	global_store_dwordx4 v10, v[244:247], s[28:29] offset:16
	s_nop 1
	s_and_b64 exec, s[8:9], s[16:17]
	v_lshlrev_b32_e32 v14, 16, v248
	v_and_b32_e32 v15, 0xffff0000, v248
	v_lshlrev_b32_e32 v16, 16, v249
	v_and_b32_e32 v17, 0xffff0000, v249
	global_store_dwordx4 v11, v[14:17], s[28:29]
	v_lshlrev_b32_e32 v248, 16, v250
	v_and_b32_e32 v249, 0xffff0000, v250
	v_lshlrev_b32_e32 v250, 16, v251
	v_and_b32_e32 v251, 0xffff0000, v251
	global_store_dwordx4 v11, v[248:251], s[28:29] offset:16
	s_nop 1
	s_and_b64 exec, s[8:9], s[18:19]
	v_lshlrev_b32_e32 v14, 16, v252
	v_and_b32_e32 v15, 0xffff0000, v252
	v_lshlrev_b32_e32 v16, 16, v253
	v_and_b32_e32 v17, 0xffff0000, v253
	global_store_dwordx4 v12, v[14:17], s[28:29]
	v_lshlrev_b32_e32 v252, 16, v254
	v_and_b32_e32 v253, 0xffff0000, v254
	v_lshlrev_b32_e32 v254, 16, v255
	v_and_b32_e32 v255, 0xffff0000, v255
	global_store_dwordx4 v12, v[252:255], s[28:29] offset:16
	s_nop 1
	s_mov_b64 exec, s[8:9]
	v_add_u32_e32 v1, s10, v4
	v_cmp_gt_u32_e32 vcc, s5, v1
	s_and_b64 exec, exec, vcc
	s_cbranch_execnz .Lsdnc_loop

.LBB0_545:
	v_ashrrev_i32_e32 v4, 7, v48
	v_ashrrev_i32_e32 v5, 31, v4
	v_lshlrev_b64 v[6:7], 14, v[4:5]
	v_lshl_add_u64 v[8:9], v[2:3], 0, v[6:7]
	v_lshlrev_b32_e32 v6, 5, v4
	v_ashrrev_i32_e32 v7, 31, v6
	v_lshl_add_u64 v[10:11], v[6:7], 4, s[20:21]
	v_mov_b32_e32 v7, 0
	s_mov_b32 s10, 0
	s_mov_b64 s[18:19], 0x1000
.Lnscan_grp:
	global_load_dword v240, v[8:9], off
	global_load_dword v241, v[8:9], off offset:512
	global_load_dword v242, v[8:9], off offset:1024
	global_load_dword v243, v[8:9], off offset:1536
	global_load_dword v244, v[8:9], off offset:2048
	global_load_dword v245, v[8:9], off offset:2560
	global_load_dword v246, v[8:9], off offset:3072
	global_load_dword v247, v[8:9], off offset:3584
	global_load_dword v248, v[10:11], off
	global_load_dword v249, v[10:11], off offset:16
	global_load_dword v250, v[10:11], off offset:32
	global_load_dword v251, v[10:11], off offset:48
	global_load_dword v252, v[10:11], off offset:64
	global_load_dword v253, v[10:11], off offset:80
	global_load_dword v254, v[10:11], off offset:96
	global_load_dword v255, v[10:11], off offset:112
	v_add_co_u32_e32 v12, vcc, 0x40000, v8
	s_nop 1
	v_addc_co_u32_e32 v13, vcc, 0, v9, vcc
	s_add_i32 s10, s10, 1
	s_waitcnt vmcnt(0)
	global_store_dword v[12:13], v7, off
	v_fma_f32 v7, v7, v248, v240
	global_store_dword v[12:13], v7, off offset:512
	v_fma_f32 v7, v7, v249, v241
	global_store_dword v[12:13], v7, off offset:1024
	v_fma_f32 v7, v7, v250, v242
	global_store_dword v[12:13], v7, off offset:1536
	v_fma_f32 v7, v7, v251, v243
	global_store_dword v[12:13], v7, off offset:2048
	v_fma_f32 v7, v7, v252, v244
	global_store_dword v[12:13], v7, off offset:2560
	v_fma_f32 v7, v7, v253, v245
	global_store_dword v[12:13], v7, off offset:3072
	v_fma_f32 v7, v7, v254, v246
	global_store_dword v[12:13], v7, off offset:3584
	v_fma_f32 v7, v7, v255, v247
	v_lshl_add_u64 v[8:9], v[8:9], 0, s[18:19]
	v_add_co_u32_e32 v10, vcc, 0x80, v10
	s_nop 1
	v_addc_co_u32_e32 v11, vcc, 0, v11, vcc
	s_cmp_eq_u32 s10, 4
	s_cbranch_scc0 .Lnscan_grp
	v_lshlrev_b64 v[8:9], 9, v[4:5]
	v_lshl_add_u64 v[8:9], s[28:29], 0, v[8:9]
	v_lshl_add_u64 v[10:11], v[8:9], 0, v[0:1]
	v_add_co_u32_e32 v10, vcc, 0x4c24000, v10
	s_nop 1
	v_addc_co_u32_e32 v11, vcc, 0, v11, vcc
	global_store_dword v[10:11], v7, off
	s_and_saveexec_b64 s[10:11], s[4:5]
	s_cbranch_execz .LBB0_544
	v_or_b32_e32 v6, 31, v6
	v_ashrrev_i32_e32 v7, 31, v6
	v_lshl_add_u64 v[6:7], v[6:7], 4, s[20:21]
	global_load_dword v6, v[6:7], off offset:8
	v_mad_i64_i32 v[4:5], s[18:19], v4, s13, v[8:9]
	v_add_co_u32_e32 v4, vcc, 0x4c26000, v4
	s_nop 1
	v_addc_co_u32_e32 v5, vcc, 0, v5, vcc
	s_waitcnt vmcnt(0)
	global_store_dword v[4:5], v6, off
	s_branch .LBB0_544

.LBB0_1005:
	s_or_b64 exec, exec, s[0:1]
	s_mov_b32 s4, 0x2c0000
	v_cmp_gt_i32_e32 vcc, s4, v144
	s_and_saveexec_b64 s[0:1], vcc
	v_readlane_b32 s19, v239, 6
	s_cbranch_execz .LBB0_1013
	s_mov_b32 s4, 0xba2e8ba3
	s_mov_b32 s5, 0x58000
	v_mov_b32_e32 v0, v144
.Lsffn_loop:
	s_mov_b64 s[6:7], exec
	v_cmp_gt_u32_e64 s[8:9], s5, v0
	v_lshrrev_b32_e32 v12, 7, v0
	v_mul_hi_u32 v12, v12, s4
	v_lshrrev_b32_e32 v12, 3, v12
	v_mul_u32_u24_e32 v13, 0x580, v12
	v_sub_u32_e32 v13, v0, v13
	v_and_b32_e32 v14, 1, v12
	v_sub_u32_e32 v4, v12, v14
	v_lshl_add_u32 v4, v4, 2, v14
	v_add_u32_e32 v4, 0x2006, v4
	v_mul_u32_u24_e32 v4, 0x5800, v4
	v_lshl_add_u32 v4, v13, 4, v4
	v_mul_u32_u24_e32 v8, 0xb000, v12
	v_lshl_add_u32 v8, v13, 5, v8
	v_add_u32_e32 v8, 0xd13e840, v8
	v_add_u32_e32 v1, s22, v0
	v_cmp_gt_u32_e64 s[10:11], s5, v1
	v_lshrrev_b32_e32 v12, 7, v1
	v_mul_hi_u32 v12, v12, s4
	v_lshrrev_b32_e32 v12, 3, v12
	v_mul_u32_u24_e32 v13, 0x580, v12
	v_sub_u32_e32 v13, v1, v13
	v_and_b32_e32 v14, 1, v12
	v_sub_u32_e32 v5, v12, v14
	v_lshl_add_u32 v5, v5, 2, v14
	v_add_u32_e32 v5, 0x2006, v5
	v_mul_u32_u24_e32 v5, 0x5800, v5
	v_lshl_add_u32 v5, v13, 4, v5
	v_mul_u32_u24_e32 v9, 0xb000, v12
	v_lshl_add_u32 v9, v13, 5, v9
	v_add_u32_e32 v9, 0xd13e840, v9
	v_add_u32_e32 v2, s22, v1
	v_cmp_gt_u32_e64 s[12:13], s5, v2
	v_lshrrev_b32_e32 v12, 7, v2
	v_mul_hi_u32 v12, v12, s4
	v_lshrrev_b32_e32 v12, 3, v12
	v_mul_u32_u24_e32 v13, 0x580, v12
	v_sub_u32_e32 v13, v2, v13
	v_and_b32_e32 v14, 1, v12
	v_sub_u32_e32 v6, v12, v14
	v_lshl_add_u32 v6, v6, 2, v14
	v_add_u32_e32 v6, 0x2006, v6
	v_mul_u32_u24_e32 v6, 0x5800, v6
	v_lshl_add_u32 v6, v13, 4, v6
	v_mul_u32_u24_e32 v10, 0xb000, v12
	v_lshl_add_u32 v10, v13, 5, v10
	v_add_u32_e32 v10, 0xd13e840, v10
	v_add_u32_e32 v3, s22, v2
	v_cmp_gt_u32_e64 s[14:15], s5, v3
	v_lshrrev_b32_e32 v12, 7, v3
	v_mul_hi_u32 v12, v12, s4
	v_lshrrev_b32_e32 v12, 3, v12
	v_mul_u32_u24_e32 v13, 0x580, v12
	v_sub_u32_e32 v13, v3, v13
	v_and_b32_e32 v14, 1, v12
	v_sub_u32_e32 v7, v12, v14
	v_lshl_add_u32 v7, v7, 2, v14
	v_add_u32_e32 v7, 0x2006, v7
	v_mul_u32_u24_e32 v7, 0x5800, v7
	v_lshl_add_u32 v7, v13, 4, v7
	v_mul_u32_u24_e32 v11, 0xb000, v12
	v_lshl_add_u32 v11, v13, 5, v11
	v_add_u32_e32 v11, 0xd13e840, v11
	s_and_b64 exec, s[6:7], s[8:9]
	global_load_dwordx4 v[240:243], v4, s[30:31]
	s_and_b64 exec, s[6:7], s[10:11]
	global_load_dwordx4 v[244:247], v5, s[30:31]
	s_and_b64 exec, s[6:7], s[12:13]
	global_load_dwordx4 v[248:251], v6, s[30:31]
	s_and_b64 exec, s[6:7], s[14:15]
	global_load_dwordx4 v[252:255], v7, s[30:31]
	s_waitcnt vmcnt(0)
	s_and_b64 exec, s[6:7], s[8:9]
	v_lshlrev_b32_e32 v12, 16, v240
	v_and_b32_e32 v13, 0xffff0000, v240
	v_lshlrev_b32_e32 v14, 16, v241
	v_and_b32_e32 v15, 0xffff0000, v241
	global_store_dwordx4 v8, v[12:15], s[28:29]
	v_lshlrev_b32_e32 v240, 16, v242
	v_and_b32_e32 v241, 0xffff0000, v242
	v_lshlrev_b32_e32 v242, 16, v243
	v_and_b32_e32 v243, 0xffff0000, v243
	global_store_dwordx4 v8, v[240:243], s[28:29] offset:16
	s_nop 1
	s_and_b64 exec, s[6:7], s[10:11]
	v_lshlrev_b32_e32 v12, 16, v244
	v_and_b32_e32 v13, 0xffff0000, v244
	v_lshlrev_b32_e32 v14, 16, v245
	v_and_b32_e32 v15, 0xffff0000, v245
	global_store_dwordx4 v9, v[12:15], s[28:29]
	v_lshlrev_b32_e32 v244, 16, v246
	v_and_b32_e32 v245, 0xffff0000, v246
	v_lshlrev_b32_e32 v246, 16, v247
	v_and_b32_e32 v247, 0xffff0000, v247
	global_store_dwordx4 v9, v[244:247], s[28:29] offset:16
	s_nop 1
	s_and_b64 exec, s[6:7], s[12:13]
	v_lshlrev_b32_e32 v12, 16, v248
	v_and_b32_e32 v13, 0xffff0000, v248
	v_lshlrev_b32_e32 v14, 16, v249
	v_and_b32_e32 v15, 0xffff0000, v249
	global_store_dwordx4 v10, v[12:15], s[28:29]
	v_lshlrev_b32_e32 v248, 16, v250
	v_and_b32_e32 v249, 0xffff0000, v250
	v_lshlrev_b32_e32 v250, 16, v251
	v_and_b32_e32 v251, 0xffff0000, v251
	global_store_dwordx4 v10, v[248:251], s[28:29] offset:16
	s_nop 1
	s_and_b64 exec, s[6:7], s[14:15]
	v_lshlrev_b32_e32 v12, 16, v252
	v_and_b32_e32 v13, 0xffff0000, v252
	v_lshlrev_b32_e32 v14, 16, v253
	v_and_b32_e32 v15, 0xffff0000, v253
	global_store_dwordx4 v11, v[12:15], s[28:29]
	v_lshlrev_b32_e32 v252, 16, v254
	v_and_b32_e32 v253, 0xffff0000, v254
	v_lshlrev_b32_e32 v254, 16, v255
	v_and_b32_e32 v255, 0xffff0000, v255
	global_store_dwordx4 v11, v[252:255], s[28:29] offset:16
	s_nop 1
	s_mov_b64 exec, s[6:7]
	v_add_u32_e32 v0, s22, v3
	v_cmp_gt_u32_e32 vcc, s5, v0
	s_and_b64 exec, exec, vcc
	s_cbranch_execnz .Lsffn_loop

	.amdhsa_kernel _Z9hymba_fwd6Params
		.amdhsa_group_segment_fixed_size 0
		.amdhsa_private_segment_fixed_size 0
		.amdhsa_kernarg_size 464
		.amdhsa_user_sgpr_count 2
		.amdhsa_user_sgpr_dispatch_ptr 0
		.amdhsa_user_sgpr_queue_ptr 0
		.amdhsa_user_sgpr_kernarg_segment_ptr 1
		.amdhsa_user_sgpr_dispatch_id 0
		.amdhsa_user_sgpr_kernarg_preload_length 0
		.amdhsa_user_sgpr_kernarg_preload_offset 0
		.amdhsa_user_sgpr_private_segment_size 0
		.amdhsa_uses_dynamic_stack 0
		.amdhsa_enable_private_segment 0
		.amdhsa_system_sgpr_workgroup_id_x 1
		.amdhsa_system_sgpr_workgroup_id_y 0
		.amdhsa_system_sgpr_workgroup_id_z 0
		.amdhsa_system_sgpr_workgroup_info 0
		.amdhsa_system_vgpr_workitem_id 2
		.amdhsa_next_free_vgpr 256
		.amdhsa_next_free_sgpr 98
		.amdhsa_accum_offset 256
		.amdhsa_reserve_vcc 1
		.amdhsa_float_round_mode_32 0
		.amdhsa_float_round_mode_16_64 0
		.amdhsa_float_denorm_mode_32 3
		.amdhsa_float_denorm_mode_16_64 3
		.amdhsa_dx10_clamp 1
		.amdhsa_ieee_mode 1
		.amdhsa_fp16_overflow 0
		.amdhsa_tg_split 0
		.amdhsa_exception_fp_ieee_invalid_op 0
		.amdhsa_exception_fp_denorm_src 0
		.amdhsa_exception_fp_ieee_div_zero 0
		.amdhsa_exception_fp_ieee_overflow 0
		.amdhsa_exception_fp_ieee_underflow 0
		.amdhsa_exception_fp_ieee_inexact 0
		.amdhsa_exception_int_div_zero 0
	.end_amdhsa_kernel

amdhsa.kernels:
  - .agpr_count:     0
    .args:
      - .offset:         0
        .size:           208
        .value_kind:     by_value
      - .offset:         208
        .size:           4
        .value_kind:     hidden_block_count_x
      - .offset:         212
        .size:           4
        .value_kind:     hidden_block_count_y
      - .offset:         216
        .size:           4
        .value_kind:     hidden_block_count_z
      - .offset:         220
        .size:           2
        .value_kind:     hidden_group_size_x
      - .offset:         222
        .size:           2
        .value_kind:     hidden_group_size_y
      - .offset:         224
        .size:           2
        .value_kind:     hidden_group_size_z
      - .offset:         226
        .size:           2
        .value_kind:     hidden_remainder_x
      - .offset:         228
        .size:           2
        .value_kind:     hidden_remainder_y
      - .offset:         230
        .size:           2
        .value_kind:     hidden_remainder_z
      - .offset:         248
        .size:           8
        .value_kind:     hidden_global_offset_x
      - .offset:         256
        .size:           8
        .value_kind:     hidden_global_offset_y
      - .offset:         264
        .size:           8
        .value_kind:     hidden_global_offset_z
      - .offset:         272
        .size:           2
        .value_kind:     hidden_grid_dims
      - .offset:         296
        .size:           8
        .value_kind:     hidden_multigrid_sync_arg
      - .offset:         328
        .size:           4
        .value_kind:     hidden_dynamic_lds_size
    .group_segment_fixed_size: 0
    .kernarg_segment_align: 8
    .kernarg_segment_size: 464
    .language:       OpenCL C
    .language_version:
      - 2
      - 0
    .max_flat_workgroup_size: 512
    .name:           _Z9hymba_fwd6Params
    .private_segment_fixed_size: 0
    .sgpr_count:     104
    .sgpr_spill_count: 161
    .symbol:         _Z9hymba_fwd6Params.kd
    .uniform_work_group_size: 1
    .uses_dynamic_stack: false
    .vgpr_count:     256
    .vgpr_spill_count: 0
    .wavefront_size: 64
